# same GEMM MFMA ordering and setprio/NA-mask edits, without the diff-attention S-wave interleave
# baseline (speedup 1.0000x reference)
.LBB0_1360:
	s_nop 9
	v_max_f32_e32 v101, v5, v5
	v_max_f32_e32 v103, v4, v4
	v_max_f32_e32 v101, v103, v101
	v_max3_f32 v101, v101, v6, v7
	v_max3_f32 v101, v101, v8, v9
	v_max3_f32 v101, v101, v10, v11
	v_max3_f32 v101, v101, v12, v13
	v_max3_f32 v101, v101, v14, v15
	v_max3_f32 v101, v101, v16, v17
	v_max3_f32 v101, v101, v18, v19
	v_max3_f32 v101, v101, v20, v21
	v_max3_f32 v101, v101, v22, v23
	v_max3_f32 v101, v101, v24, v25
	v_max3_f32 v101, v101, v26, v27
	v_max3_f32 v101, v101, v28, v29
	v_max3_f32 v101, v101, v30, v31
	v_max3_f32 v101, v101, v32, v33
	v_max3_f32 v101, v101, v34, v35
	v_mov_b32_e32 v103, v101
	s_nop 1
	v_permlane32_swap_b32_e32 v101, v103
	v_max_f32_e32 v103, v103, v103
	v_max_f32_e32 v101, v101, v101
	v_max_f32_e32 v101, v101, v103
	v_sub_f32_e32 v103, v101, v102
	v_cmp_ge_f32_e32 vcc, s34, v103
	v_max_f32_e32 v103, v102, v102
	v_max_f32_e32 v103, v103, v101
	v_sub_f32_e32 v101, v102, v103
	v_mul_f32_e32 v101, 0x3fb8aa3b, v101
	v_exp_f32_e32 v101, v101
	s_cmp_eq_u64 vcc, exec
	s_cselect_b64 vcc, -1, 0
	v_cndmask_b32_e64 v101, v101, 1.0, vcc
	v_cmp_gt_f32_e64 s[0:1], 1.0, v101
	s_cmp_lg_u64 s[0:1], 0
	s_cselect_b64 s[0:1], -1, 0
	s_and_b64 s[78:79], s[0:1], s[2:3]
	s_and_saveexec_b64 s[20:21], s[78:79]
	ds_write_b32 v2, v101
	s_or_b64 exec, exec, s[20:21]
	s_and_saveexec_b64 s[20:21], s[4:5]
	v_cndmask_b32_e64 v104, 0, 1, s[0:1]
	s_add_i32 s0, s59, 0
	s_add_i32 s0, s0, 0x20000
	v_mov_b32_e32 v105, s0
	ds_write_b32 v105, v104
	s_or_b64 exec, exec, s[20:21]
	s_add_i32 s0, s70, -3
	s_cmp_ge_u32 s0, s36
	v_add_u32_e32 v104, s72, v184
	s_cbranch_scc1 .LBB0_1366
	s_mul_hi_u32 s0, s68, 0xaaaaaaab
	s_lshr_b32 s0, s0, 1
	s_mul_i32 s0, s0, 0xc000
	v_subrev_u32_e32 v36, s0, v190
	v_subrev_u32_e32 v40, s0, v192
	v_subrev_u32_e32 v41, s0, v194
	v_subrev_u32_e32 v42, s0, v196
	v_subrev_u32_e32 v43, s0, v198
	v_subrev_u32_e32 v44, s0, v200
	v_subrev_u32_e32 v45, s0, v202
	v_subrev_u32_e32 v46, s0, v203
	v_add_u32_e32 v47, v104, v36
	v_add_u32_e32 v40, v104, v40
	ds_read_b128 v[36:39], v47
	ds_read_b128 v[52:55], v47 offset:8192
	ds_read_b128 v[106:109], v40
	ds_read_b128 v[110:113], v40 offset:8192
	v_add_u32_e32 v40, v104, v41
	ds_read_b128 v[114:117], v40
	ds_read_b128 v[118:121], v40 offset:8192
	v_add_u32_e32 v40, v104, v42
	ds_read_b128 v[122:125], v40
	ds_read_b128 v[126:129], v40 offset:8192
	v_add_u32_e32 v40, v104, v43
	ds_read_b128 v[130:133], v40
	ds_read_b128 v[134:137], v40 offset:8192
	v_add_u32_e32 v40, v104, v44
	ds_read_b128 v[138:141], v40
	ds_read_b128 v[142:145], v40 offset:8192
	v_add_u32_e32 v40, v104, v45
	ds_read_b128 v[146:149], v40
	ds_read_b128 v[150:153], v40 offset:8192
	v_add_u32_e32 v40, v104, v46
	ds_read_b128 v[214:217], v40
	ds_read_b128 v[218:221], v40 offset:8192
	s_waitcnt lgkmcnt(0)
	v_mfma_f32_32x32x16_bf16 v[36:51], v[36:39], v[68:71], 0
	v_mfma_f32_32x32x16_bf16 v[52:67], v[52:55], v[68:71], 0
	s_waitcnt lgkmcnt(13)
	v_mfma_f32_32x32x16_bf16 v[36:51], v[106:109], v[72:75], v[36:51]
	s_waitcnt lgkmcnt(12)
	v_mfma_f32_32x32x16_bf16 v[52:67], v[110:113], v[72:75], v[52:67]
	s_waitcnt lgkmcnt(11)
	v_mfma_f32_32x32x16_bf16 v[36:51], v[114:117], v[76:79], v[36:51]
	s_waitcnt lgkmcnt(10)
	v_mfma_f32_32x32x16_bf16 v[52:67], v[118:121], v[76:79], v[52:67]
	s_waitcnt lgkmcnt(9)
	v_mfma_f32_32x32x16_bf16 v[36:51], v[122:125], v[80:83], v[36:51]
	s_waitcnt lgkmcnt(8)
	v_mfma_f32_32x32x16_bf16 v[52:67], v[126:129], v[80:83], v[52:67]
	s_waitcnt lgkmcnt(7)
	v_mfma_f32_32x32x16_bf16 v[36:51], v[130:133], v[84:87], v[36:51]
	s_waitcnt lgkmcnt(6)
	v_mfma_f32_32x32x16_bf16 v[52:67], v[134:137], v[84:87], v[52:67]
	s_waitcnt lgkmcnt(5)
	v_mfma_f32_32x32x16_bf16 v[36:51], v[138:141], v[88:91], v[36:51]
	s_waitcnt lgkmcnt(4)
	v_mfma_f32_32x32x16_bf16 v[52:67], v[142:145], v[88:91], v[52:67]
	s_waitcnt lgkmcnt(3)
	v_mfma_f32_32x32x16_bf16 v[36:51], v[146:149], v[92:95], v[36:51]
	s_waitcnt lgkmcnt(2)
	v_mfma_f32_32x32x16_bf16 v[52:67], v[150:153], v[92:95], v[52:67]
	s_waitcnt lgkmcnt(1)
	v_mfma_f32_32x32x16_bf16 v[36:51], v[214:217], v[96:99], v[36:51]
	s_waitcnt lgkmcnt(0)
	v_mfma_f32_32x32x16_bf16 v[52:67], v[218:221], v[96:99], v[52:67]
.LBB0_1366:
	v_cndmask_b32_e32 v102, v103, v102, vcc
	v_mul_f32_e32 v103, 0xbfb8aa3b, v102
	v_fmamk_f32 v4, v4, 0x3fb8aa3b, v103
	v_fmamk_f32 v5, v5, 0x3fb8aa3b, v103
	v_exp_f32_e32 v4, v4
	v_fmamk_f32 v6, v6, 0x3fb8aa3b, v103
	v_exp_f32_e32 v5, v5
	v_fmamk_f32 v7, v7, 0x3fb8aa3b, v103
	v_exp_f32_e32 v6, v6
	v_fmamk_f32 v8, v8, 0x3fb8aa3b, v103
	v_fmamk_f32 v9, v9, 0x3fb8aa3b, v103
	v_fmamk_f32 v10, v10, 0x3fb8aa3b, v103
	v_fmamk_f32 v11, v11, 0x3fb8aa3b, v103
	v_fmamk_f32 v12, v12, 0x3fb8aa3b, v103
	v_fmamk_f32 v13, v13, 0x3fb8aa3b, v103
	v_fmamk_f32 v14, v14, 0x3fb8aa3b, v103
	v_fmamk_f32 v15, v15, 0x3fb8aa3b, v103
	v_fmamk_f32 v16, v16, 0x3fb8aa3b, v103
	v_fmamk_f32 v17, v17, 0x3fb8aa3b, v103
	v_fmamk_f32 v18, v18, 0x3fb8aa3b, v103
	v_fmamk_f32 v19, v19, 0x3fb8aa3b, v103
	v_fmamk_f32 v20, v20, 0x3fb8aa3b, v103
	v_fmamk_f32 v21, v21, 0x3fb8aa3b, v103
	v_fmamk_f32 v22, v22, 0x3fb8aa3b, v103
	v_fmamk_f32 v23, v23, 0x3fb8aa3b, v103
	v_fmamk_f32 v24, v24, 0x3fb8aa3b, v103
	v_fmamk_f32 v25, v25, 0x3fb8aa3b, v103
	v_fmamk_f32 v26, v26, 0x3fb8aa3b, v103
	v_fmamk_f32 v27, v27, 0x3fb8aa3b, v103
	v_fmamk_f32 v28, v28, 0x3fb8aa3b, v103
	v_fmamk_f32 v29, v29, 0x3fb8aa3b, v103
	v_fmamk_f32 v30, v30, 0x3fb8aa3b, v103
	v_fmamk_f32 v31, v31, 0x3fb8aa3b, v103
	v_fmamk_f32 v32, v32, 0x3fb8aa3b, v103
	v_fmamk_f32 v33, v33, 0x3fb8aa3b, v103
	v_fmamk_f32 v34, v34, 0x3fb8aa3b, v103
	v_fmac_f32_e32 v103, 0x3fb8aa3b, v35
	v_exp_f32_e32 v7, v7
	v_exp_f32_e32 v8, v8
	v_exp_f32_e32 v35, v103
	v_add_f32_e32 v103, 0, v4
	v_exp_f32_e32 v9, v9
	v_add_f32_e32 v103, v5, v103
	v_exp_f32_e32 v10, v10
	v_add_f32_e32 v103, v6, v103
	v_exp_f32_e32 v11, v11
	v_add_f32_e32 v103, v7, v103
	v_exp_f32_e32 v12, v12
	v_add_f32_e32 v103, v8, v103
	v_exp_f32_e32 v13, v13
	v_add_f32_e32 v103, v9, v103
	v_exp_f32_e32 v14, v14
	v_add_f32_e32 v103, v10, v103
	v_exp_f32_e32 v15, v15
	v_add_f32_e32 v103, v11, v103
	v_exp_f32_e32 v16, v16
	v_add_f32_e32 v103, v12, v103
	v_exp_f32_e32 v17, v17
	v_add_f32_e32 v103, v13, v103
	v_exp_f32_e32 v18, v18
	v_add_f32_e32 v103, v14, v103
	v_exp_f32_e32 v19, v19
	v_add_f32_e32 v103, v15, v103
	v_exp_f32_e32 v20, v20
	v_add_f32_e32 v103, v16, v103
	v_exp_f32_e32 v21, v21
	v_add_f32_e32 v103, v17, v103
	v_exp_f32_e32 v22, v22
	v_add_f32_e32 v103, v18, v103
	v_exp_f32_e32 v23, v23
	v_add_f32_e32 v103, v19, v103
	v_exp_f32_e32 v24, v24
	v_add_f32_e32 v103, v20, v103
	v_exp_f32_e32 v25, v25
	v_add_f32_e32 v103, v21, v103
	v_exp_f32_e32 v26, v26
	v_add_f32_e32 v103, v22, v103
	v_exp_f32_e32 v27, v27
	v_add_f32_e32 v103, v23, v103
	v_exp_f32_e32 v28, v28
	v_add_f32_e32 v103, v24, v103
	v_exp_f32_e32 v29, v29
	v_add_f32_e32 v103, v25, v103
	v_exp_f32_e32 v30, v30
	v_add_f32_e32 v103, v26, v103
	v_exp_f32_e32 v31, v31
	v_add_f32_e32 v103, v27, v103
	v_exp_f32_e32 v32, v32
	v_add_f32_e32 v103, v28, v103
	v_exp_f32_e32 v33, v33
	v_add_f32_e32 v103, v29, v103
	v_exp_f32_e32 v34, v34
	v_add_f32_e32 v103, v30, v103
	v_add_f32_e32 v103, v31, v103
	v_add_f32_e32 v103, v32, v103
	v_add_f32_e32 v103, v33, v103
	v_add_f32_e32 v103, v34, v103
	s_waitcnt lgkmcnt(0)
	s_barrier
	v_add_f32_e32 v105, v35, v103
	v_mov_b32_e32 v106, v105
	v_cvt_pk_bf16_f32 v108, v4, v5
	v_cvt_pk_bf16_f32 v109, v6, v7
	v_cvt_pk_bf16_f32 v110, v8, v9
	v_cvt_pk_bf16_f32 v111, v10, v11
	s_add_i32 s0, s70, -1
	s_nop 0
	v_permlane32_swap_b32_e32 v105, v106
	v_permlane32_swap_b32_e32 v108, v110
	v_permlane32_swap_b32_e32 v109, v111
	v_cvt_pk_bf16_f32 v112, v12, v13
	v_cvt_pk_bf16_f32 v113, v14, v15
	v_cvt_pk_bf16_f32 v114, v16, v17
	v_cvt_pk_bf16_f32 v115, v18, v19
	v_cvt_pk_bf16_f32 v116, v20, v21
	v_cvt_pk_bf16_f32 v117, v22, v23
	v_cvt_pk_bf16_f32 v118, v24, v25
	v_cvt_pk_bf16_f32 v119, v26, v27
	v_cvt_pk_bf16_f32 v120, v28, v29
	v_cvt_pk_bf16_f32 v121, v30, v31
	v_cvt_pk_bf16_f32 v122, v32, v33
	v_cvt_pk_bf16_f32 v123, v34, v35
	v_add_u32_e32 v103, s57, v161
	s_cmp_ge_u32 s0, s36
	s_mov_b64 s[0:1], -1
	v_permlane32_swap_b32_e32 v112, v114
	v_permlane32_swap_b32_e32 v113, v115
	v_permlane32_swap_b32_e32 v116, v118
	v_permlane32_swap_b32_e32 v117, v119
	v_permlane32_swap_b32_e32 v120, v122
	v_permlane32_swap_b32_e32 v121, v123
	ds_write_b128 v103, v[108:111]
	ds_write_b128 v103, v[112:115] offset:1024
	ds_write_b128 v103, v[116:119] offset:2048
	ds_write_b128 v103, v[120:123] offset:3072
	s_cbranch_scc0 .LBB0_1368
	s_waitcnt vmcnt(0)
	s_mov_b64 s[0:1], 0

.LBB0_1373:
	s_mul_hi_u32 s0, s69, 0xaaaaaaab
	s_lshr_b32 s0, s0, 1
	s_mul_i32 s0, s0, 0xc000
	v_subrev_u32_e32 v8, s0, v186
	v_subrev_u32_e32 v9, s0, v189
	v_subrev_u32_e32 v10, s0, v191
	v_subrev_u32_e32 v11, s0, v193
	v_subrev_u32_e32 v12, s0, v195
	v_subrev_u32_e32 v13, s0, v197
	v_subrev_u32_e32 v14, s0, v199
	v_subrev_u32_e32 v4, s0, v201
	v_add_u32_e32 v15, v104, v4
	v_add_u32_e32 v14, v104, v14
	v_add_u32_e32 v13, v104, v13
	v_add_u32_e32 v12, v104, v12
	v_add_u32_e32 v11, v104, v11
	v_add_u32_e32 v10, v104, v10
	v_add_u32_e32 v9, v104, v9
	v_add_u32_e32 v8, v104, v8
	ds_read_b128 v[4:7], v15
	ds_read_b128 v[20:23], v15 offset:8192
	ds_read_b128 v[110:113], v14
	ds_read_b128 v[114:117], v14 offset:8192
	ds_read_b128 v[118:121], v13
	ds_read_b128 v[122:125], v13 offset:8192
	ds_read_b128 v[126:129], v12
	ds_read_b128 v[130:133], v12 offset:8192
	ds_read_b128 v[134:137], v11
	ds_read_b128 v[138:141], v11 offset:8192
	ds_read_b128 v[142:145], v10
	ds_read_b128 v[146:149], v10 offset:8192
	ds_read_b128 v[150:153], v9
	ds_read_b128 v[214:217], v9 offset:8192
	ds_read_b128 v[218:221], v8
	ds_read_b128 v[222:225], v8 offset:8192
	s_waitcnt lgkmcnt(0)
	v_mfma_f32_32x32x16_bf16 v[4:19], v[4:7], v[68:71], 0
	v_mfma_f32_32x32x16_bf16 v[20:35], v[20:23], v[68:71], 0
	v_mfma_f32_32x32x16_bf16 v[4:19], v[110:113], v[72:75], v[4:19]
	v_mfma_f32_32x32x16_bf16 v[20:35], v[114:117], v[72:75], v[20:35]
	v_mfma_f32_32x32x16_bf16 v[4:19], v[118:121], v[76:79], v[4:19]
	v_mfma_f32_32x32x16_bf16 v[20:35], v[122:125], v[76:79], v[20:35]
	v_mfma_f32_32x32x16_bf16 v[4:19], v[126:129], v[80:83], v[4:19]
	v_mfma_f32_32x32x16_bf16 v[20:35], v[130:133], v[80:83], v[20:35]
	v_mfma_f32_32x32x16_bf16 v[4:19], v[134:137], v[84:87], v[4:19]
	v_mfma_f32_32x32x16_bf16 v[20:35], v[138:141], v[84:87], v[20:35]
	v_mfma_f32_32x32x16_bf16 v[4:19], v[142:145], v[88:91], v[4:19]
	v_mfma_f32_32x32x16_bf16 v[20:35], v[146:149], v[88:91], v[20:35]
	v_mfma_f32_32x32x16_bf16 v[4:19], v[150:153], v[92:95], v[4:19]
	v_mfma_f32_32x32x16_bf16 v[20:35], v[214:217], v[92:95], v[20:35]
	v_mfma_f32_32x32x16_bf16 v[4:19], v[218:221], v[96:99], v[4:19]
	v_mfma_f32_32x32x16_bf16 v[20:35], v[222:225], v[96:99], v[20:35]
.LBB0_1374:
	v_cndmask_b32_e32 v102, v108, v102, vcc
	v_mul_f32_e32 v104, 0xbfb8aa3b, v102
	v_fmamk_f32 v36, v36, 0x3fb8aa3b, v104
	v_fmamk_f32 v37, v37, 0x3fb8aa3b, v104
	v_exp_f32_e32 v36, v36
	v_fmamk_f32 v38, v38, 0x3fb8aa3b, v104
	v_exp_f32_e32 v37, v37
	v_fmamk_f32 v39, v39, 0x3fb8aa3b, v104
	v_exp_f32_e32 v38, v38
	v_fmamk_f32 v40, v40, 0x3fb8aa3b, v104
	v_exp_f32_e32 v39, v39
	v_add_f32_e32 v105, v105, v106
	v_fmamk_f32 v41, v41, 0x3fb8aa3b, v104
	v_exp_f32_e32 v40, v40
	v_fmac_f32_e32 v105, v100, v101
	v_add_f32_e32 v100, 0, v36
	v_fmamk_f32 v42, v42, 0x3fb8aa3b, v104
	v_exp_f32_e32 v41, v41
	v_add_f32_e32 v100, v37, v100
	v_fmamk_f32 v43, v43, 0x3fb8aa3b, v104
	v_exp_f32_e32 v42, v42
	v_add_f32_e32 v100, v38, v100
	v_fmamk_f32 v44, v44, 0x3fb8aa3b, v104
	v_exp_f32_e32 v43, v43
	v_add_f32_e32 v100, v39, v100
	v_fmamk_f32 v45, v45, 0x3fb8aa3b, v104
	v_exp_f32_e32 v44, v44
	v_add_f32_e32 v100, v40, v100
	v_fmamk_f32 v46, v46, 0x3fb8aa3b, v104
	v_exp_f32_e32 v45, v45
	v_add_f32_e32 v100, v41, v100
	v_fmamk_f32 v47, v47, 0x3fb8aa3b, v104
	v_exp_f32_e32 v46, v46
	v_add_f32_e32 v100, v42, v100
	v_fmamk_f32 v48, v48, 0x3fb8aa3b, v104
	v_exp_f32_e32 v47, v47
	v_add_f32_e32 v100, v43, v100
	v_fmamk_f32 v49, v49, 0x3fb8aa3b, v104
	v_exp_f32_e32 v48, v48
	v_add_f32_e32 v100, v44, v100
	v_fmamk_f32 v50, v50, 0x3fb8aa3b, v104
	v_exp_f32_e32 v49, v49
	v_add_f32_e32 v100, v45, v100
	v_fmamk_f32 v51, v51, 0x3fb8aa3b, v104
	v_exp_f32_e32 v50, v50
	v_add_f32_e32 v100, v46, v100
	v_fmamk_f32 v52, v52, 0x3fb8aa3b, v104
	v_exp_f32_e32 v51, v51
	v_add_f32_e32 v100, v47, v100
	v_fmamk_f32 v53, v53, 0x3fb8aa3b, v104
	v_exp_f32_e32 v52, v52
	v_add_f32_e32 v100, v48, v100
	v_fmamk_f32 v54, v54, 0x3fb8aa3b, v104
	v_exp_f32_e32 v53, v53
	v_add_f32_e32 v100, v49, v100
	v_fmamk_f32 v55, v55, 0x3fb8aa3b, v104
	v_exp_f32_e32 v54, v54
	v_add_f32_e32 v100, v50, v100
	v_fmamk_f32 v56, v56, 0x3fb8aa3b, v104
	v_exp_f32_e32 v55, v55
	v_add_f32_e32 v100, v51, v100
	v_fmamk_f32 v57, v57, 0x3fb8aa3b, v104
	v_exp_f32_e32 v56, v56
	v_add_f32_e32 v100, v52, v100
	v_fmamk_f32 v58, v58, 0x3fb8aa3b, v104
	v_exp_f32_e32 v57, v57
	v_add_f32_e32 v100, v53, v100
	v_fmamk_f32 v59, v59, 0x3fb8aa3b, v104
	v_exp_f32_e32 v58, v58
	v_add_f32_e32 v100, v54, v100
	v_fmamk_f32 v60, v60, 0x3fb8aa3b, v104
	v_exp_f32_e32 v59, v59
	v_add_f32_e32 v100, v55, v100
	v_fmamk_f32 v61, v61, 0x3fb8aa3b, v104
	v_exp_f32_e32 v60, v60
	v_add_f32_e32 v100, v56, v100
	v_fmamk_f32 v62, v62, 0x3fb8aa3b, v104
	v_exp_f32_e32 v61, v61
	v_add_f32_e32 v100, v57, v100
	v_fmamk_f32 v63, v63, 0x3fb8aa3b, v104
	v_exp_f32_e32 v62, v62
	v_add_f32_e32 v100, v58, v100
	v_fmamk_f32 v64, v64, 0x3fb8aa3b, v104
	v_exp_f32_e32 v63, v63
	v_add_f32_e32 v100, v59, v100
	v_fmamk_f32 v65, v65, 0x3fb8aa3b, v104
	v_exp_f32_e32 v64, v64
	v_add_f32_e32 v100, v60, v100
	v_fmamk_f32 v66, v66, 0x3fb8aa3b, v104
	v_exp_f32_e32 v65, v65
	v_add_f32_e32 v100, v61, v100
	v_fmac_f32_e32 v104, 0x3fb8aa3b, v67
	v_exp_f32_e32 v66, v66
	v_add_f32_e32 v100, v62, v100
	v_exp_f32_e32 v67, v104
	v_add_f32_e32 v100, v63, v100
	v_add_f32_e32 v100, v64, v100
	v_add_f32_e32 v100, v65, v100
	v_add_f32_e32 v100, v66, v100
	v_add_f32_e32 v100, v67, v100
	v_mov_b32_e32 v101, v100
	s_nop 1
	v_permlane32_swap_b32_e32 v100, v101
	s_waitcnt lgkmcnt(0)
	s_barrier
	v_add_f32_e32 v100, v100, v101
	s_cmp_eq_u32 s73, s72
	v_fmac_f32_e32 v100, v105, v107
	v_cvt_pk_bf16_f32 v104, v36, v37
	v_cvt_pk_bf16_f32 v105, v38, v39
	v_cvt_pk_bf16_f32 v106, v40, v41
	v_cvt_pk_bf16_f32 v107, v42, v43
	s_cselect_b64 s[0:1], -1, 0
	v_permlane32_swap_b32_e32 v104, v106
	v_permlane32_swap_b32_e32 v105, v107
	v_cvt_pk_bf16_f32 v108, v44, v45
	v_cvt_pk_bf16_f32 v109, v46, v47
	v_cvt_pk_bf16_f32 v110, v48, v49
	v_cvt_pk_bf16_f32 v111, v50, v51
	v_cvt_pk_bf16_f32 v112, v52, v53
	v_cvt_pk_bf16_f32 v113, v54, v55
	v_cvt_pk_bf16_f32 v114, v56, v57
	v_cvt_pk_bf16_f32 v115, v58, v59
	v_cvt_pk_bf16_f32 v116, v60, v61
	v_cvt_pk_bf16_f32 v117, v62, v63
	v_cvt_pk_bf16_f32 v118, v64, v65
	v_cvt_pk_bf16_f32 v119, v66, v67
	s_and_b64 s[78:79], s[0:1], s[2:3]
	v_permlane32_swap_b32_e32 v108, v110
	v_permlane32_swap_b32_e32 v109, v111
	v_permlane32_swap_b32_e32 v112, v114
	v_permlane32_swap_b32_e32 v113, v115
	v_permlane32_swap_b32_e32 v116, v118
	v_permlane32_swap_b32_e32 v117, v119
	ds_write_b128 v103, v[104:107]
	ds_write_b128 v103, v[108:111] offset:1024
	ds_write_b128 v103, v[112:115] offset:2048
	ds_write_b128 v103, v[116:119] offset:3072
	s_and_saveexec_b64 s[0:1], s[78:79]
	s_cbranch_execz .LBB0_1379
	ds_write_b32 v2, v100 offset:128
	s_or_b64 exec, exec, s[0:1]
	s_cmp_ge_u32 s70, s36
	s_mov_b64 s[0:1], -1
	s_cbranch_scc1 .LBB0_1380

.LBB0_1392:
	s_nop 9
	v_max_f32_e32 v101, v5, v5
	v_max_f32_e32 v103, v4, v4
	v_max_f32_e32 v101, v103, v101
	v_max3_f32 v101, v101, v6, v7
	v_max3_f32 v101, v101, v8, v9
	v_max3_f32 v101, v101, v10, v11
	v_max3_f32 v101, v101, v12, v13
	v_max3_f32 v101, v101, v14, v15
	v_max3_f32 v101, v101, v16, v17
	v_max3_f32 v101, v101, v18, v19
	v_max3_f32 v101, v101, v20, v21
	v_max3_f32 v101, v101, v22, v23
	v_max3_f32 v101, v101, v24, v25
	v_max3_f32 v101, v101, v26, v27
	v_max3_f32 v101, v101, v28, v29
	v_max3_f32 v101, v101, v30, v31
	v_max3_f32 v101, v101, v32, v33
	v_max3_f32 v101, v101, v34, v35
	v_mov_b32_e32 v103, v101
	s_nop 1
	v_permlane32_swap_b32_e32 v101, v103
	v_max_f32_e32 v103, v103, v103
	v_max_f32_e32 v101, v101, v101
	v_max_f32_e32 v101, v101, v103
	v_sub_f32_e32 v103, v101, v102
	v_cmp_ge_f32_e32 vcc, s34, v103
	v_max_f32_e32 v103, v102, v102
	v_max_f32_e32 v103, v103, v101
	v_sub_f32_e32 v101, v102, v103
	v_mul_f32_e32 v101, 0x3fb8aa3b, v101
	v_exp_f32_e32 v101, v101
	s_cmp_eq_u64 vcc, exec
	s_cselect_b64 vcc, -1, 0
	v_cndmask_b32_e64 v101, v101, 1.0, vcc
	v_cmp_gt_f32_e64 s[0:1], 1.0, v101
	s_cmp_lg_u64 s[0:1], 0
	s_cselect_b64 s[0:1], -1, 0
	s_and_b64 s[66:67], s[0:1], s[2:3]
	s_and_saveexec_b64 s[14:15], s[66:67]
	ds_write_b32 v2, v101
	s_or_b64 exec, exec, s[14:15]
	s_and_saveexec_b64 s[14:15], s[4:5]
	v_cndmask_b32_e64 v104, 0, 1, s[0:1]
	s_add_i32 s0, s19, 0
	s_add_i32 s0, s0, 0x20000
	v_mov_b32_e32 v105, s0
	ds_write_b32 v105, v104
	s_or_b64 exec, exec, s[14:15]
	s_add_i32 s0, s58, -3
	s_cmp_ge_u32 s0, s36
	v_add_u32_e32 v104, s60, v184
	s_cbranch_scc1 .LBB0_1398
	s_mul_hi_u32 s0, s56, 0xaaaaaaab
	s_lshr_b32 s0, s0, 1
	s_mul_i32 s0, s0, 0xc000
	v_subrev_u32_e32 v36, s0, v190
	v_subrev_u32_e32 v40, s0, v192
	v_subrev_u32_e32 v41, s0, v194
	v_subrev_u32_e32 v42, s0, v196
	v_subrev_u32_e32 v43, s0, v198
	v_subrev_u32_e32 v44, s0, v200
	v_subrev_u32_e32 v45, s0, v202
	v_subrev_u32_e32 v46, s0, v203
	v_add_u32_e32 v47, v104, v36
	v_add_u32_e32 v40, v104, v40
	ds_read_b128 v[36:39], v47
	ds_read_b128 v[52:55], v47 offset:8192
	ds_read_b128 v[106:109], v40
	ds_read_b128 v[110:113], v40 offset:8192
	v_add_u32_e32 v40, v104, v41
	ds_read_b128 v[114:117], v40
	ds_read_b128 v[118:121], v40 offset:8192
	v_add_u32_e32 v40, v104, v42
	ds_read_b128 v[122:125], v40
	ds_read_b128 v[126:129], v40 offset:8192
	v_add_u32_e32 v40, v104, v43
	ds_read_b128 v[130:133], v40
	ds_read_b128 v[134:137], v40 offset:8192
	v_add_u32_e32 v40, v104, v44
	ds_read_b128 v[138:141], v40
	ds_read_b128 v[142:145], v40 offset:8192
	v_add_u32_e32 v40, v104, v45
	ds_read_b128 v[146:149], v40
	ds_read_b128 v[150:153], v40 offset:8192
	v_add_u32_e32 v40, v104, v46
	ds_read_b128 v[154:157], v40
	ds_read_b128 v[214:217], v40 offset:8192
	s_waitcnt lgkmcnt(0)
	v_mfma_f32_32x32x16_bf16 v[36:51], v[36:39], v[68:71], 0
	v_mfma_f32_32x32x16_bf16 v[52:67], v[52:55], v[68:71], 0
	s_waitcnt lgkmcnt(13)
	v_mfma_f32_32x32x16_bf16 v[36:51], v[106:109], v[72:75], v[36:51]
	s_waitcnt lgkmcnt(12)
	v_mfma_f32_32x32x16_bf16 v[52:67], v[110:113], v[72:75], v[52:67]
	s_waitcnt lgkmcnt(11)
	v_mfma_f32_32x32x16_bf16 v[36:51], v[114:117], v[76:79], v[36:51]
	s_waitcnt lgkmcnt(10)
	v_mfma_f32_32x32x16_bf16 v[52:67], v[118:121], v[76:79], v[52:67]
	s_waitcnt lgkmcnt(9)
	v_mfma_f32_32x32x16_bf16 v[36:51], v[122:125], v[80:83], v[36:51]
	s_waitcnt lgkmcnt(8)
	v_mfma_f32_32x32x16_bf16 v[52:67], v[126:129], v[80:83], v[52:67]
	s_waitcnt lgkmcnt(7)
	v_mfma_f32_32x32x16_bf16 v[36:51], v[130:133], v[84:87], v[36:51]
	s_waitcnt lgkmcnt(6)
	v_mfma_f32_32x32x16_bf16 v[52:67], v[134:137], v[84:87], v[52:67]
	s_waitcnt lgkmcnt(5)
	v_mfma_f32_32x32x16_bf16 v[36:51], v[138:141], v[88:91], v[36:51]
	s_waitcnt lgkmcnt(4)
	v_mfma_f32_32x32x16_bf16 v[52:67], v[142:145], v[88:91], v[52:67]
	s_waitcnt lgkmcnt(3)
	v_mfma_f32_32x32x16_bf16 v[36:51], v[146:149], v[92:95], v[36:51]
	s_waitcnt lgkmcnt(2)
	v_mfma_f32_32x32x16_bf16 v[52:67], v[150:153], v[92:95], v[52:67]
	s_waitcnt lgkmcnt(1)
	v_mfma_f32_32x32x16_bf16 v[36:51], v[154:157], v[96:99], v[36:51]
	s_waitcnt lgkmcnt(0)
	v_mfma_f32_32x32x16_bf16 v[52:67], v[214:217], v[96:99], v[52:67]
.LBB0_1398:
	v_cndmask_b32_e32 v102, v103, v102, vcc
	v_mul_f32_e32 v103, 0xbfb8aa3b, v102
	v_fmamk_f32 v4, v4, 0x3fb8aa3b, v103
	v_fmamk_f32 v5, v5, 0x3fb8aa3b, v103
	v_exp_f32_e32 v4, v4
	v_fmamk_f32 v6, v6, 0x3fb8aa3b, v103
	v_exp_f32_e32 v5, v5
	v_fmamk_f32 v7, v7, 0x3fb8aa3b, v103
	v_exp_f32_e32 v6, v6
	v_fmamk_f32 v8, v8, 0x3fb8aa3b, v103
	v_fmamk_f32 v9, v9, 0x3fb8aa3b, v103
	v_fmamk_f32 v10, v10, 0x3fb8aa3b, v103
	v_fmamk_f32 v11, v11, 0x3fb8aa3b, v103
	v_fmamk_f32 v12, v12, 0x3fb8aa3b, v103
	v_fmamk_f32 v13, v13, 0x3fb8aa3b, v103
	v_fmamk_f32 v14, v14, 0x3fb8aa3b, v103
	v_fmamk_f32 v15, v15, 0x3fb8aa3b, v103
	v_fmamk_f32 v16, v16, 0x3fb8aa3b, v103
	v_fmamk_f32 v17, v17, 0x3fb8aa3b, v103
	v_fmamk_f32 v18, v18, 0x3fb8aa3b, v103
	v_fmamk_f32 v19, v19, 0x3fb8aa3b, v103
	v_fmamk_f32 v20, v20, 0x3fb8aa3b, v103
	v_fmamk_f32 v21, v21, 0x3fb8aa3b, v103
	v_fmamk_f32 v22, v22, 0x3fb8aa3b, v103
	v_fmamk_f32 v23, v23, 0x3fb8aa3b, v103
	v_fmamk_f32 v24, v24, 0x3fb8aa3b, v103
	v_fmamk_f32 v25, v25, 0x3fb8aa3b, v103
	v_fmamk_f32 v26, v26, 0x3fb8aa3b, v103
	v_fmamk_f32 v27, v27, 0x3fb8aa3b, v103
	v_fmamk_f32 v28, v28, 0x3fb8aa3b, v103
	v_fmamk_f32 v29, v29, 0x3fb8aa3b, v103
	v_fmamk_f32 v30, v30, 0x3fb8aa3b, v103
	v_fmamk_f32 v31, v31, 0x3fb8aa3b, v103
	v_fmamk_f32 v32, v32, 0x3fb8aa3b, v103
	v_fmamk_f32 v33, v33, 0x3fb8aa3b, v103
	v_fmamk_f32 v34, v34, 0x3fb8aa3b, v103
	v_fmac_f32_e32 v103, 0x3fb8aa3b, v35
	v_exp_f32_e32 v7, v7
	v_exp_f32_e32 v8, v8
	v_exp_f32_e32 v35, v103
	v_add_f32_e32 v103, 0, v4
	v_exp_f32_e32 v9, v9
	v_add_f32_e32 v103, v5, v103
	v_exp_f32_e32 v10, v10
	v_add_f32_e32 v103, v6, v103
	v_exp_f32_e32 v11, v11
	v_add_f32_e32 v103, v7, v103
	v_exp_f32_e32 v12, v12
	v_add_f32_e32 v103, v8, v103
	v_exp_f32_e32 v13, v13
	v_add_f32_e32 v103, v9, v103
	v_exp_f32_e32 v14, v14
	v_add_f32_e32 v103, v10, v103
	v_exp_f32_e32 v15, v15
	v_add_f32_e32 v103, v11, v103
	v_exp_f32_e32 v16, v16
	v_add_f32_e32 v103, v12, v103
	v_exp_f32_e32 v17, v17
	v_add_f32_e32 v103, v13, v103
	v_exp_f32_e32 v18, v18
	v_add_f32_e32 v103, v14, v103
	v_exp_f32_e32 v19, v19
	v_add_f32_e32 v103, v15, v103
	v_exp_f32_e32 v20, v20
	v_add_f32_e32 v103, v16, v103
	v_exp_f32_e32 v21, v21
	v_add_f32_e32 v103, v17, v103
	v_exp_f32_e32 v22, v22
	v_add_f32_e32 v103, v18, v103
	v_exp_f32_e32 v23, v23
	v_add_f32_e32 v103, v19, v103
	v_exp_f32_e32 v24, v24
	v_add_f32_e32 v103, v20, v103
	v_exp_f32_e32 v25, v25
	v_add_f32_e32 v103, v21, v103
	v_exp_f32_e32 v26, v26
	v_add_f32_e32 v103, v22, v103
	v_exp_f32_e32 v27, v27
	v_add_f32_e32 v103, v23, v103
	v_exp_f32_e32 v28, v28
	v_add_f32_e32 v103, v24, v103
	v_exp_f32_e32 v29, v29
	v_add_f32_e32 v103, v25, v103
	v_exp_f32_e32 v30, v30
	v_add_f32_e32 v103, v26, v103
	v_exp_f32_e32 v31, v31
	v_add_f32_e32 v103, v27, v103
	v_exp_f32_e32 v32, v32
	v_add_f32_e32 v103, v28, v103
	v_exp_f32_e32 v33, v33
	v_add_f32_e32 v103, v29, v103
	v_exp_f32_e32 v34, v34
	v_add_f32_e32 v103, v30, v103
	v_add_f32_e32 v103, v31, v103
	v_add_f32_e32 v103, v32, v103
	v_add_f32_e32 v103, v33, v103
	v_add_f32_e32 v103, v34, v103
	s_waitcnt lgkmcnt(0)
	s_barrier
	v_add_f32_e32 v105, v35, v103
	v_mov_b32_e32 v106, v105
	v_cvt_pk_bf16_f32 v108, v4, v5
	v_cvt_pk_bf16_f32 v109, v6, v7
	v_cvt_pk_bf16_f32 v110, v8, v9
	v_cvt_pk_bf16_f32 v111, v10, v11
	s_add_i32 s0, s58, -1
	s_nop 0
	v_permlane32_swap_b32_e32 v105, v106
	v_permlane32_swap_b32_e32 v108, v110
	v_permlane32_swap_b32_e32 v109, v111
	v_cvt_pk_bf16_f32 v112, v12, v13
	v_cvt_pk_bf16_f32 v113, v14, v15
	v_cvt_pk_bf16_f32 v114, v16, v17
	v_cvt_pk_bf16_f32 v115, v18, v19
	v_cvt_pk_bf16_f32 v116, v20, v21
	v_cvt_pk_bf16_f32 v117, v22, v23
	v_cvt_pk_bf16_f32 v118, v24, v25
	v_cvt_pk_bf16_f32 v119, v26, v27
	v_cvt_pk_bf16_f32 v120, v28, v29
	v_cvt_pk_bf16_f32 v121, v30, v31
	v_cvt_pk_bf16_f32 v122, v32, v33
	v_cvt_pk_bf16_f32 v123, v34, v35
	v_add_u32_e32 v103, s18, v161
	s_cmp_ge_u32 s0, s36
	s_mov_b64 s[0:1], -1
	v_permlane32_swap_b32_e32 v112, v114
	v_permlane32_swap_b32_e32 v113, v115
	v_permlane32_swap_b32_e32 v116, v118
	v_permlane32_swap_b32_e32 v117, v119
	v_permlane32_swap_b32_e32 v120, v122
	v_permlane32_swap_b32_e32 v121, v123
	ds_write_b128 v103, v[108:111]
	ds_write_b128 v103, v[112:115] offset:1024
	ds_write_b128 v103, v[116:119] offset:2048
	ds_write_b128 v103, v[120:123] offset:3072
	s_cbranch_scc0 .LBB0_1400
	s_waitcnt vmcnt(0)
	s_mov_b64 s[0:1], 0

.LBB0_1405:
	s_mul_hi_u32 s0, s57, 0xaaaaaaab
	s_lshr_b32 s0, s0, 1
	s_mul_i32 s0, s0, 0xc000
	v_subrev_u32_e32 v8, s0, v186
	v_subrev_u32_e32 v9, s0, v189
	v_subrev_u32_e32 v10, s0, v191
	v_subrev_u32_e32 v11, s0, v193
	v_subrev_u32_e32 v12, s0, v195
	v_subrev_u32_e32 v13, s0, v197
	v_subrev_u32_e32 v14, s0, v199
	v_subrev_u32_e32 v4, s0, v201
	v_add_u32_e32 v15, v104, v4
	v_add_u32_e32 v14, v104, v14
	v_add_u32_e32 v13, v104, v13
	v_add_u32_e32 v12, v104, v12
	v_add_u32_e32 v11, v104, v11
	v_add_u32_e32 v10, v104, v10
	v_add_u32_e32 v9, v104, v9
	v_add_u32_e32 v8, v104, v8
	ds_read_b128 v[4:7], v15
	ds_read_b128 v[20:23], v15 offset:8192
	ds_read_b128 v[110:113], v14
	ds_read_b128 v[114:117], v14 offset:8192
	ds_read_b128 v[118:121], v13
	ds_read_b128 v[122:125], v13 offset:8192
	ds_read_b128 v[126:129], v12
	ds_read_b128 v[130:133], v12 offset:8192
	ds_read_b128 v[134:137], v11
	ds_read_b128 v[138:141], v11 offset:8192
	ds_read_b128 v[142:145], v10
	ds_read_b128 v[146:149], v10 offset:8192
	ds_read_b128 v[150:153], v9
	ds_read_b128 v[154:157], v9 offset:8192
	ds_read_b128 v[214:217], v8
	ds_read_b128 v[218:221], v8 offset:8192
	s_waitcnt lgkmcnt(0)
	v_mfma_f32_32x32x16_bf16 v[4:19], v[4:7], v[68:71], 0
	v_mfma_f32_32x32x16_bf16 v[20:35], v[20:23], v[68:71], 0
	v_mfma_f32_32x32x16_bf16 v[4:19], v[110:113], v[72:75], v[4:19]
	v_mfma_f32_32x32x16_bf16 v[20:35], v[114:117], v[72:75], v[20:35]
	v_mfma_f32_32x32x16_bf16 v[4:19], v[118:121], v[76:79], v[4:19]
	v_mfma_f32_32x32x16_bf16 v[20:35], v[122:125], v[76:79], v[20:35]
	v_mfma_f32_32x32x16_bf16 v[4:19], v[126:129], v[80:83], v[4:19]
	v_mfma_f32_32x32x16_bf16 v[20:35], v[130:133], v[80:83], v[20:35]
	v_mfma_f32_32x32x16_bf16 v[4:19], v[134:137], v[84:87], v[4:19]
	v_mfma_f32_32x32x16_bf16 v[20:35], v[138:141], v[84:87], v[20:35]
	v_mfma_f32_32x32x16_bf16 v[4:19], v[142:145], v[88:91], v[4:19]
	v_mfma_f32_32x32x16_bf16 v[20:35], v[146:149], v[88:91], v[20:35]
	v_mfma_f32_32x32x16_bf16 v[4:19], v[150:153], v[92:95], v[4:19]
	v_mfma_f32_32x32x16_bf16 v[20:35], v[154:157], v[92:95], v[20:35]
	v_mfma_f32_32x32x16_bf16 v[4:19], v[214:217], v[96:99], v[4:19]
	v_mfma_f32_32x32x16_bf16 v[20:35], v[218:221], v[96:99], v[20:35]
.LBB0_1406:
	v_cndmask_b32_e32 v102, v108, v102, vcc
	v_mul_f32_e32 v104, 0xbfb8aa3b, v102
	v_fmamk_f32 v36, v36, 0x3fb8aa3b, v104
	v_fmamk_f32 v37, v37, 0x3fb8aa3b, v104
	v_exp_f32_e32 v36, v36
	v_fmamk_f32 v38, v38, 0x3fb8aa3b, v104
	v_exp_f32_e32 v37, v37
	v_fmamk_f32 v39, v39, 0x3fb8aa3b, v104
	v_exp_f32_e32 v38, v38
	v_fmamk_f32 v40, v40, 0x3fb8aa3b, v104
	v_exp_f32_e32 v39, v39
	v_add_f32_e32 v105, v105, v106
	v_fmamk_f32 v41, v41, 0x3fb8aa3b, v104
	v_exp_f32_e32 v40, v40
	v_fmac_f32_e32 v105, v100, v101
	v_add_f32_e32 v100, 0, v36
	v_fmamk_f32 v42, v42, 0x3fb8aa3b, v104
	v_exp_f32_e32 v41, v41
	v_add_f32_e32 v100, v37, v100
	v_fmamk_f32 v43, v43, 0x3fb8aa3b, v104
	v_exp_f32_e32 v42, v42
	v_add_f32_e32 v100, v38, v100
	v_fmamk_f32 v44, v44, 0x3fb8aa3b, v104
	v_exp_f32_e32 v43, v43
	v_add_f32_e32 v100, v39, v100
	v_fmamk_f32 v45, v45, 0x3fb8aa3b, v104
	v_exp_f32_e32 v44, v44
	v_add_f32_e32 v100, v40, v100
	v_fmamk_f32 v46, v46, 0x3fb8aa3b, v104
	v_exp_f32_e32 v45, v45
	v_add_f32_e32 v100, v41, v100
	v_fmamk_f32 v47, v47, 0x3fb8aa3b, v104
	v_exp_f32_e32 v46, v46
	v_add_f32_e32 v100, v42, v100
	v_fmamk_f32 v48, v48, 0x3fb8aa3b, v104
	v_exp_f32_e32 v47, v47
	v_add_f32_e32 v100, v43, v100
	v_fmamk_f32 v49, v49, 0x3fb8aa3b, v104
	v_exp_f32_e32 v48, v48
	v_add_f32_e32 v100, v44, v100
	v_fmamk_f32 v50, v50, 0x3fb8aa3b, v104
	v_exp_f32_e32 v49, v49
	v_add_f32_e32 v100, v45, v100
	v_fmamk_f32 v51, v51, 0x3fb8aa3b, v104
	v_exp_f32_e32 v50, v50
	v_add_f32_e32 v100, v46, v100
	v_fmamk_f32 v52, v52, 0x3fb8aa3b, v104
	v_exp_f32_e32 v51, v51
	v_add_f32_e32 v100, v47, v100
	v_fmamk_f32 v53, v53, 0x3fb8aa3b, v104
	v_exp_f32_e32 v52, v52
	v_add_f32_e32 v100, v48, v100
	v_fmamk_f32 v54, v54, 0x3fb8aa3b, v104
	v_exp_f32_e32 v53, v53
	v_add_f32_e32 v100, v49, v100
	v_fmamk_f32 v55, v55, 0x3fb8aa3b, v104
	v_exp_f32_e32 v54, v54
	v_add_f32_e32 v100, v50, v100
	v_fmamk_f32 v56, v56, 0x3fb8aa3b, v104
	v_exp_f32_e32 v55, v55
	v_add_f32_e32 v100, v51, v100
	v_fmamk_f32 v57, v57, 0x3fb8aa3b, v104
	v_exp_f32_e32 v56, v56
	v_add_f32_e32 v100, v52, v100
	v_fmamk_f32 v58, v58, 0x3fb8aa3b, v104
	v_exp_f32_e32 v57, v57
	v_add_f32_e32 v100, v53, v100
	v_fmamk_f32 v59, v59, 0x3fb8aa3b, v104
	v_exp_f32_e32 v58, v58
	v_add_f32_e32 v100, v54, v100
	v_fmamk_f32 v60, v60, 0x3fb8aa3b, v104
	v_exp_f32_e32 v59, v59
	v_add_f32_e32 v100, v55, v100
	v_fmamk_f32 v61, v61, 0x3fb8aa3b, v104
	v_exp_f32_e32 v60, v60
	v_add_f32_e32 v100, v56, v100
	v_fmamk_f32 v62, v62, 0x3fb8aa3b, v104
	v_exp_f32_e32 v61, v61
	v_add_f32_e32 v100, v57, v100
	v_fmamk_f32 v63, v63, 0x3fb8aa3b, v104
	v_exp_f32_e32 v62, v62
	v_add_f32_e32 v100, v58, v100
	v_fmamk_f32 v64, v64, 0x3fb8aa3b, v104
	v_exp_f32_e32 v63, v63
	v_add_f32_e32 v100, v59, v100
	v_fmamk_f32 v65, v65, 0x3fb8aa3b, v104
	v_exp_f32_e32 v64, v64
	v_add_f32_e32 v100, v60, v100
	v_fmamk_f32 v66, v66, 0x3fb8aa3b, v104
	v_exp_f32_e32 v65, v65
	v_add_f32_e32 v100, v61, v100
	v_fmac_f32_e32 v104, 0x3fb8aa3b, v67
	v_exp_f32_e32 v66, v66
	v_add_f32_e32 v100, v62, v100
	v_exp_f32_e32 v67, v104
	v_add_f32_e32 v100, v63, v100
	v_add_f32_e32 v100, v64, v100
	v_add_f32_e32 v100, v65, v100
	v_add_f32_e32 v100, v66, v100
	v_add_f32_e32 v100, v67, v100
	v_mov_b32_e32 v101, v100
	s_nop 1
	v_permlane32_swap_b32_e32 v100, v101
	s_waitcnt lgkmcnt(0)
	s_barrier
	v_add_f32_e32 v100, v100, v101
	s_cmp_eq_u32 s20, s60
	v_fmac_f32_e32 v100, v105, v107
	v_cvt_pk_bf16_f32 v104, v36, v37
	v_cvt_pk_bf16_f32 v105, v38, v39
	v_cvt_pk_bf16_f32 v106, v40, v41
	v_cvt_pk_bf16_f32 v107, v42, v43
	s_cselect_b64 s[0:1], -1, 0
	v_permlane32_swap_b32_e32 v104, v106
	v_permlane32_swap_b32_e32 v105, v107
	v_cvt_pk_bf16_f32 v108, v44, v45
	v_cvt_pk_bf16_f32 v109, v46, v47
	v_cvt_pk_bf16_f32 v110, v48, v49
	v_cvt_pk_bf16_f32 v111, v50, v51
	v_cvt_pk_bf16_f32 v112, v52, v53
	v_cvt_pk_bf16_f32 v113, v54, v55
	v_cvt_pk_bf16_f32 v114, v56, v57
	v_cvt_pk_bf16_f32 v115, v58, v59
	v_cvt_pk_bf16_f32 v116, v60, v61
	v_cvt_pk_bf16_f32 v117, v62, v63
	v_cvt_pk_bf16_f32 v118, v64, v65
	v_cvt_pk_bf16_f32 v119, v66, v67
	s_and_b64 s[66:67], s[0:1], s[2:3]
	v_permlane32_swap_b32_e32 v108, v110
	v_permlane32_swap_b32_e32 v109, v111
	v_permlane32_swap_b32_e32 v112, v114
	v_permlane32_swap_b32_e32 v113, v115
	v_permlane32_swap_b32_e32 v116, v118
	v_permlane32_swap_b32_e32 v117, v119
	ds_write_b128 v103, v[104:107]
	ds_write_b128 v103, v[108:111] offset:1024
	ds_write_b128 v103, v[112:115] offset:2048
	ds_write_b128 v103, v[116:119] offset:3072
	s_and_saveexec_b64 s[0:1], s[66:67]
	s_cbranch_execz .LBB0_1411
	ds_write_b32 v2, v100 offset:128
	s_or_b64 exec, exec, s[0:1]
	s_cmp_ge_u32 s58, s36
	s_mov_b64 s[0:1], -1
	s_cbranch_scc1 .LBB0_1412
